# DA unit head: lambda-vector loads get their own registers; their wait and products move behind the issue of all 12 Q/K/V tile loads
# speedup vs baseline: 1.0036x; 1.0036x over previous
; __device__ __forceinline__ float bflo(unsigned w) { return __uint_as_float(w << 16); }
; __device__ void da_unit(char* lds, const Params& p, int layer, int unit) {
;     int tid_ = threadIdx.x; asm volatile("" : "+v"(tid_)); const int tid = tid_, lane = tid & 63, wid = __builtin_amdgcn_readfirstlane(tid >> 6), r = lane & 31, h2 = lane >> 5;
;     const int c = wid & 1, qg = wid >> 1;
;     const int g8 = unit >> 3, bh = (unit & 7) * 4 + (g8 >> 4), qb = g8 & 15, b = bh >> 2, h = bh & 3;
;     const float slope2 = exp2f(-2.0f * (float)(h + 1)) * LOG2E;
;     const float qscale = 0.125f * LOG2E;
;     float lam;
;     {
;         const float v1 = p.lq1[layer * 64 + lane] * p.lk1[layer * 64 + lane], v2 = p.lq2[layer * 64 + lane] * p.lk2[layer * 64 + lane];
;         float s1 = v1, s2 = v2;
; #pragma unroll
;         for (int s = 32; s >= 1; s >>= 1) { s1 += __shfl_xor(s1, s); s2 += __shfl_xor(s2, s); }
;         lam = __expf(s1) - __expf(s2) + p.lam_init[layer];
;     }
;     const int q0 = qb * 128 + qg * 32;
;     const size_t tokq = (size_t)b * SEQ + q0 + r;
;     bf16x8 qf[4];
; #pragma unroll
;     for (int t = 0; t < 4; ++t) {
;         const u32x4 w = *(const u32x4*)(p.z + ZS_QD + ((size_t)(bh * 2048 + q0 + r)) * 128 + c * 64 + t * 16 + h2 * 8);
;         u32x4 o;
;         o.x = cvt_pk_bf16(bflo(w.x) * qscale, bfhi(w.x) * qscale); o.y = cvt_pk_bf16(bflo(w.y) * qscale, bfhi(w.y) * qscale);
;         o.z = cvt_pk_bf16(bflo(w.z) * qscale, bfhi(w.z) * qscale); o.w = cvt_pk_bf16(bflo(w.w) * qscale, bfhi(w.w) * qscale);
;         qf[t] = __builtin_bit_cast(bf16x8, o);
;     }
;     f32x16 O[4], Bs;
; #pragma unroll
;     for (int k = 0; k < 4; ++k)
; #pragma unroll
;         for (int e = 0; e < 16; ++e) O[k][e] = 0.f;
; #pragma unroll
;     for (int e = 0; e < 16; ++e) Bs[e] = -slope2 * (float)(16 * (e >> 3) + (e & 7));
;     float mrow = -1e30f, lrow = 0.f;
;     const float qrel = (float)(8 * h2) - (float)(q0 + r);
;     const bf16_t* Kg = p.z + ZS_KD + ((size_t)bh * 2048) * 128 + tid * 8;
;     const bf16_t* Vg = p.vT + VS_VD + ((size_t)bh * 32) * 8192 + tid * 8;
;     const int kr_ = tid >> 4, kc_ = tid & 15, vr_ = tid >> 3, vc_ = tid & 7;
;     constexpr int NT = SEQ / 128;
;     auto tile_of = [&](int i) { return (i < NT - qb) ? (qb + i) : (NT - 1 - i); };
;     u32x4 rk[4], rv[4];
;     {
;         const int t0 = tile_of(0);
; #pragma unroll
.LBB0_475:
	s_and_b64 vcc, exec, s[0:1]
	s_cbranch_vccz .LBB0_451
	v_mov_b32_e32 v187, v245
	v_readlane_b32 s0, v255, 36
	v_and_b32_e32 v184, 63, v187
	s_bfe_u32 s14, s21, 0x40003
	v_or_b32_e32 v152, s0, v184
	v_readlane_b32 s0, v254, 60
	v_lshlrev_b64 v[0:1], 2, v[152:153]
	v_readlane_b32 s1, v254, 61
	v_readlane_b32 s2, v254, 62
	v_readlane_b32 s3, v254, 63
	v_lshl_add_u64 v[2:3], s[0:1], 0, v[0:1]
	global_load_dword v174, v[2:3], off
	v_lshl_add_u64 v[2:3], s[2:3], 0, v[0:1]
	global_load_dword v175, v[2:3], off
	v_readlane_b32 s4, v255, 0
	v_readlane_b32 s5, v255, 1
	v_readlane_b32 s6, v255, 2
	v_readlane_b32 s7, v255, 3
	v_lshl_add_u64 v[2:3], s[4:5], 0, v[0:1]
	global_load_dword v176, v[2:3], off
	v_lshl_add_u64 v[0:1], s[6:7], 0, v[0:1]
	global_load_dword v177, v[0:1], off
	s_lshl_b32 s0, s21, 2
	s_ashr_i32 s1, s21, 7
	s_and_b32 s2, s0, 28
	v_readfirstlane_b32 s3, v187
	s_and_b32 s12, s1, 3
	s_add_i32 s6, s2, s1
	s_bfe_u32 s13, s3, 0x20006
	s_lshl_b32 s0, s14, 7
	s_not_b32 s4, s12
	s_ashr_i32 s7, s6, 31
	s_lshl_b32 s5, s13, 5
	v_and_b32_e32 v0, 64, v240
	s_ashr_i32 s10, s3, 6
	s_lshl_b32 s1, s4, 1
	s_lshl_b32 s4, s6, 11
	s_lshl_b64 s[2:3], s[6:7], 19
	s_add_i32 s7, s5, s0
	v_xor_b32_e32 v1, 32, v240
	v_add_u32_e32 v52, 64, v0
	v_and_b32_e32 v147, 31, v187
	s_lshr_b32 s15, s10, 2
	s_add_i32 s4, s7, s4
	v_cmp_lt_i32_e32 vcc, v1, v52
	s_lshl_b32 s8, s15, 7
	v_or_b32_e32 v2, s4, v147
	v_readlane_b32 s4, v254, 18
	v_cndmask_b32_e32 v1, v240, v1, vcc
	v_lshlrev_b32_e32 v0, 3, v187
	s_add_u32 s4, s4, s2
	v_readlane_b32 s5, v254, 19
	v_lshlrev_b32_e32 v244, 2, v1
	v_ashrrev_i32_e32 v1, 31, v0
	s_addc_u32 s5, s5, s3
	v_lshlrev_b64 v[0:1], 1, v[0:1]
	s_add_u32 s2, s60, s2
	v_lshl_add_u64 v[148:149], s[4:5], 0, v[0:1]
	s_addc_u32 s3, s61, s3
	s_lshl_b32 s70, s14, 15
	v_lshl_add_u64 v[164:165], v[148:149], 0, s[70:71]
	v_lshl_add_u64 v[150:151], s[2:3], 0, v[0:1]
	v_add_co_u32_e32 v0, vcc, s47, v164
	s_movk_i32 s2, 0x4000
	s_nop 0
	v_addc_co_u32_e32 v1, vcc, 0, v165, vcc
	v_add_co_u32_e32 v4, vcc, s2, v164
	s_movk_i32 s3, 0x6000
	s_nop 0
	v_addc_co_u32_e32 v5, vcc, 0, v165, vcc
	v_add_co_u32_e32 v6, vcc, s3, v164
	v_lshl_add_u64 v[166:167], v[150:151], 0, s[70:71]
	s_nop 0
	v_addc_co_u32_e32 v7, vcc, 0, v165, vcc
	global_load_dwordx4 v[18:21], v[164:165], off
	global_load_dwordx4 v[22:25], v[166:167], off
	global_load_dwordx4 v[26:29], v[0:1], off
	v_add_co_u32_e32 v0, vcc, s47, v166
	global_load_dwordx4 v[30:33], v[4:5], off
	global_load_dwordx4 v[34:37], v[6:7], off
	v_ashrrev_i32_e32 v3, 31, v2
	v_addc_co_u32_e32 v1, vcc, 0, v167, vcc
	v_lshlrev_b64 v[2:3], 8, v[2:3]
	v_add_co_u32_e32 v4, vcc, s2, v166
	s_mov_b32 s9, s71
	v_bfe_u32 v188, v187, 5, 1
	v_lshl_add_u64 v[2:3], s[58:59], 0, v[2:3]
	v_addc_co_u32_e32 v5, vcc, 0, v167, vcc
	global_load_dwordx4 v[38:41], v[0:1], off
	global_load_dwordx4 v[42:45], v[4:5], off
	v_lshlrev_b32_e32 v152, 4, v188
	v_lshl_add_u64 v[2:3], v[2:3], 0, s[8:9]
	v_lshl_add_u64 v[12:13], v[2:3], 0, v[152:153]
	v_add_co_u32_e32 v0, vcc, s3, v166
	s_movk_i32 s3, 0x110
	s_nop 0
	v_addc_co_u32_e32 v1, vcc, 0, v167, vcc
	global_load_dwordx4 v[46:49], v[0:1], off
	global_load_dwordx4 v[8:11], v[12:13], off
	global_load_dwordx4 v[4:7], v[12:13], off offset:32
	s_nop 0
	global_load_dwordx4 v[0:3], v[12:13], off offset:64
	global_load_dwordx4 v[14:17], v[12:13], off offset:96
	s_waitcnt vmcnt(12)
	v_mul_f32_e32 v226, v174, v175
	ds_bpermute_b32 v53, v244, v226
	s_waitcnt lgkmcnt(0)
	v_fmac_f32_e32 v53, v174, v175
	v_mul_f32_e32 v227, v176, v177
	ds_bpermute_b32 v54, v244, v227
	v_xor_b32_e32 v12, 16, v240
	v_cmp_lt_i32_e32 vcc, v12, v52
	s_waitcnt lgkmcnt(0)
	v_fmac_f32_e32 v54, v176, v177
	v_xor_b32_e32 v50, 8, v240
	v_cndmask_b32_e32 v12, v240, v12, vcc
	v_lshlrev_b32_e32 v12, 2, v12
	ds_bpermute_b32 v13, v12, v53
	ds_bpermute_b32 v12, v12, v54
	v_cmp_lt_i32_e32 vcc, v50, v52
	s_lshl_b32 s2, s14, 14
	s_cmp_lt_i32 s10, 4
	v_cndmask_b32_e32 v50, v240, v50, vcc
	s_waitcnt lgkmcnt(1)
	v_add_f32_e32 v13, v53, v13
	s_waitcnt lgkmcnt(0)
	v_add_f32_e32 v12, v54, v12
	v_lshlrev_b32_e32 v50, 2, v50
	ds_bpermute_b32 v51, v50, v13
	ds_bpermute_b32 v50, v50, v12
	s_waitcnt lgkmcnt(0)
	s_barrier
	v_add_f32_e32 v13, v13, v51
	v_add_f32_e32 v12, v12, v50
	v_xor_b32_e32 v50, 4, v240
	v_cmp_lt_i32_e32 vcc, v50, v52
	s_nop 1
	v_cndmask_b32_e32 v50, v240, v50, vcc
	v_lshlrev_b32_e32 v50, 2, v50
	ds_bpermute_b32 v51, v50, v13
	ds_bpermute_b32 v50, v50, v12
	s_waitcnt lgkmcnt(1)
	v_add_f32_e32 v13, v13, v51
	s_waitcnt lgkmcnt(0)
	v_add_f32_e32 v12, v12, v50
	v_xor_b32_e32 v50, 2, v240
	v_cmp_lt_i32_e32 vcc, v50, v52
	s_nop 1
	v_cndmask_b32_e32 v50, v240, v50, vcc
	v_lshlrev_b32_e32 v50, 2, v50
	ds_bpermute_b32 v51, v50, v13
	ds_bpermute_b32 v50, v50, v12
	s_waitcnt lgkmcnt(1)
	v_add_f32_e32 v170, v13, v51
	s_waitcnt lgkmcnt(0)
	v_add_f32_e32 v171, v12, v50
	v_xor_b32_e32 v12, 1, v240
	v_cmp_lt_i32_e32 vcc, v12, v52
	v_lshrrev_b32_e32 v13, 3, v187
	v_lshlrev_b32_e32 v50, 4, v187
	v_cndmask_b32_e32 v12, v240, v12, vcc
	v_lshlrev_b32_e32 v12, 2, v12
	ds_bpermute_b32 v172, v12, v170
	ds_bpermute_b32 v173, v12, v171
	v_lshrrev_b32_e32 v12, 4, v187
	v_mul_lo_u32 v182, v12, s3
	s_movk_i32 s3, 0x90
	v_and_b32_e32 v180, 0xf0, v50
	v_mul_lo_u32 v183, v13, s3
	v_add_u32_e32 v51, 0, v180
	v_and_b32_e32 v181, 0x70, v50
	v_add_u32_e32 v12, 0, v183
	v_add_u32_e32 v189, v51, v182
	v_add_u32_e32 v190, v12, v181
	s_waitcnt vmcnt(7)
	ds_write_b128 v189, v[18:21]
	ds_write_b128 v190, v[22:25] offset:34816
	ds_write_b128 v189, v[26:29] offset:8704
	s_waitcnt vmcnt(6)
	ds_write_b128 v190, v[38:41] offset:44032
	ds_write_b128 v189, v[30:33] offset:17408
	s_waitcnt vmcnt(5)
	ds_write_b128 v190, v[42:45] offset:53248
	ds_write_b128 v189, v[34:37] offset:26112
	s_waitcnt vmcnt(4)
	ds_write_b128 v190, v[46:49] offset:62464
	s_waitcnt lgkmcnt(0)
	s_barrier
	s_cbranch_scc1 .LBB0_478
	s_setprio 1
